# adds 14 of 16 rope epilogue blocks batched and C-mode neighbourhood bias LDS lookups batched
# baseline (speedup 1.0000x reference)
; DI u16 f2bf(float a) { return (u16)(pk2(a, 0.f) & 0xffffu); }
; DI int crow(int i, int h) { return (i & 3) + 8 * (i >> 2) + 4 * h; }
; template <int EPI>
; __device__ __forceinline__ void gemm_tile(const Params& p, int layer, const u16* __restrict__ A, const u16* __restrict__ Bt, int mt, int nt, char* lds) {
;     ...
;         const bool ropeA = gcb < 1024, ropeB = (gcb >= 1536 && gcb < 2816);
;         const bool latent = m0 >= NCTX;
;         if (latent && (ropeA || ropeB)) {
;           int pair, nf; bool userow; const f32x2* tab;
;           if (ropeA) { pair = (gc & 63) >> 1; nf = 16; tab = (const f32x2*)(p.ws + OFF_TABA); }
;           else       { pair = (gc & 127) >> 1; nf = 32; tab = (const f32x2*)(p.ws + OFF_TABB); }
;           userow = pair < nf;
;           const int f = userow ? pair : pair - nf;
; #pragma unroll
;           for (int e = 0; e < 16; ++e) {
;             const int gr = grb + crow(e, h);
;             const int t = gr - NCTX;
;             const int pos = userow ? (t >> 6) : (t & 63);
;             const f32x2 cs = tab[pos * nf + f];
;             const float v = acc[i][j][e];
;             const float o = __shfl_xor(v, 1);
;             const float res = (gc & 1) ? (o * cs[1] + v * cs[0]) : (v * cs[0] - o * cs[1]);
;             P[(size_t)gr * LDP + gc] = f2bf(res);
;           }
.LBB0_1307:
	s_or_b64 exec, exec, s[18:19]
	v_cndmask_b32_e64 v107, 63, 31, s[6:7]
	v_cndmask_b32_e64 v96, v140, v141, s[6:7]
	v_cndmask_b32_e64 v106, 32, 16, s[6:7]
	v_cndmask_b32_e64 v105, 5, 4, s[6:7]
	s_and_saveexec_b64 s[20:21], s[50:51]
	s_cbranch_execz .LBB0_1309
	v_lshrrev_b32_e32 v98, 1, v100
	v_mov_b32_e32 v97, v129
	v_and_b32_e32 v101, v98, v107
	s_waitcnt lgkmcnt(0)
	v_lshl_add_u64 v[98:99], s[22:23], 0, v[96:97]
	v_sub_u32_e32 v97, v101, v106
	v_ashrrev_i32_e32 v110, 6, v178
	v_cmp_lt_u32_e32 vcc, v101, v106
	v_min_u32_e32 v97, v101, v97
	v_and_b32_e32 v113, 64, v214
	v_mov_b64_e32 v[102:103], s[28:29]
	v_xor_b32_e32 v111, 1, v214
	v_add_u32_e32 v113, 64, v113
	v_cmp_lt_i32_e64 s[18:19], v111, v113
	v_and_b32_e32 v126, 1, v100
	v_ashrrev_i32_e32 v101, 31, v100
	v_cndmask_b32_e64 v111, v214, v111, s[18:19]
	v_lshlrev_b32_e32 v111, 2, v111
	v_cmp_eq_u32_e64 s[18:19], 0, v126
	v_lshlrev_b64 v[100:101], 1, v[100:101]
	s_nop 1
	v_cndmask_b32_e32 v190, v136, v110, vcc
	v_lshl_add_u32 v190, v190, v105, v97
	v_ashrrev_i32_e32 v191, 31, v190
	v_lshl_add_u64 v[190:191], v[190:191], 3, v[98:99]
	global_load_dwordx2 v[190:191], v[190:191], off
	ds_bpermute_b32 v240, v111, v80
	v_cndmask_b32_e32 v192, v177, v110, vcc
	v_lshl_add_u32 v192, v192, v105, v97
	v_ashrrev_i32_e32 v193, 31, v192
	v_lshl_add_u64 v[192:193], v[192:193], 3, v[98:99]
	global_load_dwordx2 v[192:193], v[192:193], off
	ds_bpermute_b32 v241, v111, v81
	v_cndmask_b32_e32 v194, v176, v110, vcc
	v_lshl_add_u32 v194, v194, v105, v97
	v_ashrrev_i32_e32 v195, 31, v194
	v_lshl_add_u64 v[194:195], v[194:195], 3, v[98:99]
	global_load_dwordx2 v[194:195], v[194:195], off
	ds_bpermute_b32 v242, v111, v82
	v_cndmask_b32_e32 v196, v174, v110, vcc
	v_lshl_add_u32 v196, v196, v105, v97
	v_ashrrev_i32_e32 v197, 31, v196
	v_lshl_add_u64 v[196:197], v[196:197], 3, v[98:99]
	global_load_dwordx2 v[196:197], v[196:197], off
	ds_bpermute_b32 v243, v111, v83
	v_cndmask_b32_e32 v198, v172, v110, vcc
	v_lshl_add_u32 v198, v198, v105, v97
	v_ashrrev_i32_e32 v199, 31, v198
	v_lshl_add_u64 v[198:199], v[198:199], 3, v[98:99]
	global_load_dwordx2 v[198:199], v[198:199], off
	ds_bpermute_b32 v244, v111, v84
	v_cndmask_b32_e32 v200, v169, v110, vcc
	v_lshl_add_u32 v200, v200, v105, v97
	v_ashrrev_i32_e32 v201, 31, v200
	v_lshl_add_u64 v[200:201], v[200:201], 3, v[98:99]
	global_load_dwordx2 v[200:201], v[200:201], off
	ds_bpermute_b32 v245, v111, v85
	v_cndmask_b32_e32 v202, v167, v110, vcc
	v_lshl_add_u32 v202, v202, v105, v97
	v_ashrrev_i32_e32 v203, 31, v202
	v_lshl_add_u64 v[202:203], v[202:203], 3, v[98:99]
	global_load_dwordx2 v[202:203], v[202:203], off
	ds_bpermute_b32 v246, v111, v86
	v_cndmask_b32_e32 v204, v165, v110, vcc
	v_lshl_add_u32 v204, v204, v105, v97
	v_ashrrev_i32_e32 v205, 31, v204
	v_lshl_add_u64 v[204:205], v[204:205], 3, v[98:99]
	global_load_dwordx2 v[204:205], v[204:205], off
	ds_bpermute_b32 v247, v111, v87
	v_cndmask_b32_e32 v206, v163, v110, vcc
	v_lshl_add_u32 v206, v206, v105, v97
	v_ashrrev_i32_e32 v207, 31, v206
	v_lshl_add_u64 v[206:207], v[206:207], 3, v[98:99]
	global_load_dwordx2 v[206:207], v[206:207], off
	ds_bpermute_b32 v248, v111, v88
	v_cndmask_b32_e32 v208, v161, v110, vcc
	v_lshl_add_u32 v208, v208, v105, v97
	v_ashrrev_i32_e32 v209, 31, v208
	v_lshl_add_u64 v[208:209], v[208:209], 3, v[98:99]
	global_load_dwordx2 v[208:209], v[208:209], off
	ds_bpermute_b32 v249, v111, v89
	v_cndmask_b32_e32 v216, v159, v110, vcc
	v_lshl_add_u32 v216, v216, v105, v97
	v_ashrrev_i32_e32 v217, 31, v216
	v_lshl_add_u64 v[216:217], v[216:217], 3, v[98:99]
	global_load_dwordx2 v[216:217], v[216:217], off
	ds_bpermute_b32 v250, v111, v90
	v_cndmask_b32_e32 v218, v157, v110, vcc
	v_lshl_add_u32 v218, v218, v105, v97
	v_ashrrev_i32_e32 v219, 31, v218
	v_lshl_add_u64 v[218:219], v[218:219], 3, v[98:99]
	global_load_dwordx2 v[218:219], v[218:219], off
	ds_bpermute_b32 v251, v111, v91
	v_cndmask_b32_e32 v220, v155, v110, vcc
	v_lshl_add_u32 v220, v220, v105, v97
	v_ashrrev_i32_e32 v221, 31, v220
	v_lshl_add_u64 v[220:221], v[220:221], 3, v[98:99]
	global_load_dwordx2 v[220:221], v[220:221], off
	ds_bpermute_b32 v252, v111, v92
	v_cndmask_b32_e32 v222, v153, v110, vcc
	v_lshl_add_u32 v222, v222, v105, v97
	v_ashrrev_i32_e32 v223, 31, v222
	v_lshl_add_u64 v[222:223], v[222:223], 3, v[98:99]
	global_load_dwordx2 v[222:223], v[222:223], off
	ds_bpermute_b32 v253, v111, v93
	v_cndmask_b32_e32 v224, v151, v110, vcc
	v_lshl_add_u32 v224, v224, v105, v97
	v_ashrrev_i32_e32 v225, 31, v224
	v_lshl_add_u64 v[224:225], v[224:225], 3, v[98:99]
	global_load_dwordx2 v[224:225], v[224:225], off
	ds_bpermute_b32 v254, v111, v94
	v_cndmask_b32_e32 v226, v149, v110, vcc
	v_lshl_add_u32 v226, v226, v105, v97
	v_ashrrev_i32_e32 v227, 31, v226
	v_lshl_add_u64 v[226:227], v[226:227], 3, v[98:99]
	global_load_dwordx2 v[226:227], v[226:227], off
	ds_bpermute_b32 v255, v111, v95
	s_waitcnt lgkmcnt(0)
	s_waitcnt vmcnt(15)
; DI u16 f2bf(float a) { return (u16)(pk2(a, 0.f) & 0xffffu); }
; DI int crow(int i, int h) { return (i & 3) + 8 * (i >> 2) + 4 * h; }
; template <int EPI>
; __device__ __forceinline__ void gemm_tile(const Params& p, int layer, const u16* __restrict__ A, const u16* __restrict__ Bt, int mt, int nt, char* lds) {
;     ...
; #pragma unroll
;           for (int e = 0; e < 16; ++e) {
;             const int gr = grb + crow(e, h);
;             const int t = gr - NCTX;
;             const int pos = userow ? (t >> 6) : (t & 63);
;             const f32x2 cs = tab[pos * nf + f];
;             const float v = acc[i][j][e];
;             const float o = __shfl_xor(v, 1);
;             const float res = (gc & 1) ? (o * cs[1] + v * cs[0]) : (v * cs[0] - o * cs[1]);
;             P[(size_t)gr * LDP + gc] = f2bf(res);
;           }
	v_mul_f32_e32 v240, v191, v240
	v_cndmask_b32_e64 v240, v240, -v240, s[18:19]
	v_fmac_f32_e32 v240, v80, v190
	v_cvt_pk_bf16_f32 v240, v240, s0
	v_mad_i64_i32 v[190:191], s[50:51], v170, s95, v[102:103]
	v_lshl_add_u64 v[190:191], v[190:191], 0, v[100:101]
	global_store_short v[190:191], v240, off
	s_waitcnt vmcnt(15)
	v_mul_f32_e32 v241, v193, v241
	v_cndmask_b32_e64 v241, v241, -v241, s[18:19]
	v_fmac_f32_e32 v241, v81, v192
	v_cvt_pk_bf16_f32 v241, v241, s0
	v_mad_i64_i32 v[192:193], s[50:51], v175, s95, v[102:103]
	v_lshl_add_u64 v[192:193], v[192:193], 0, v[100:101]
	global_store_short v[192:193], v241, off
	s_waitcnt vmcnt(15)
	v_mul_f32_e32 v242, v195, v242
	v_cndmask_b32_e64 v242, v242, -v242, s[18:19]
	v_fmac_f32_e32 v242, v82, v194
	v_cvt_pk_bf16_f32 v242, v242, s0
	v_mad_i64_i32 v[194:195], s[50:51], v173, s95, v[102:103]
	v_lshl_add_u64 v[194:195], v[194:195], 0, v[100:101]
	global_store_short v[194:195], v242, off
	s_waitcnt vmcnt(15)
	v_mul_f32_e32 v243, v197, v243
	v_cndmask_b32_e64 v243, v243, -v243, s[18:19]
	v_fmac_f32_e32 v243, v83, v196
	v_cvt_pk_bf16_f32 v243, v243, s0
	v_mad_i64_i32 v[196:197], s[50:51], v171, s95, v[102:103]
	v_lshl_add_u64 v[196:197], v[196:197], 0, v[100:101]
	global_store_short v[196:197], v243, off
	s_waitcnt vmcnt(15)
	v_mul_f32_e32 v244, v199, v244
	v_cndmask_b32_e64 v244, v244, -v244, s[18:19]
	v_fmac_f32_e32 v244, v84, v198
	v_cvt_pk_bf16_f32 v244, v244, s0
	v_mad_i64_i32 v[198:199], s[50:51], v168, s95, v[102:103]
	v_lshl_add_u64 v[198:199], v[198:199], 0, v[100:101]
	global_store_short v[198:199], v244, off
	s_waitcnt vmcnt(15)
	v_mul_f32_e32 v245, v201, v245
	v_cndmask_b32_e64 v245, v245, -v245, s[18:19]
	v_fmac_f32_e32 v245, v85, v200
	v_cvt_pk_bf16_f32 v245, v245, s0
	v_mad_i64_i32 v[200:201], s[50:51], v166, s95, v[102:103]
	v_lshl_add_u64 v[200:201], v[200:201], 0, v[100:101]
	global_store_short v[200:201], v245, off
	s_waitcnt vmcnt(15)
	v_mul_f32_e32 v246, v203, v246
	v_cndmask_b32_e64 v246, v246, -v246, s[18:19]
	v_fmac_f32_e32 v246, v86, v202
	v_cvt_pk_bf16_f32 v246, v246, s0
	v_mad_i64_i32 v[202:203], s[50:51], v164, s95, v[102:103]
	v_lshl_add_u64 v[202:203], v[202:203], 0, v[100:101]
	global_store_short v[202:203], v246, off
	s_waitcnt vmcnt(15)
	v_mul_f32_e32 v247, v205, v247
	v_cndmask_b32_e64 v247, v247, -v247, s[18:19]
	v_fmac_f32_e32 v247, v87, v204
	v_cvt_pk_bf16_f32 v247, v247, s0
	v_mad_i64_i32 v[204:205], s[50:51], v162, s95, v[102:103]
	v_lshl_add_u64 v[204:205], v[204:205], 0, v[100:101]
	global_store_short v[204:205], v247, off
	s_waitcnt vmcnt(15)
	v_mul_f32_e32 v248, v207, v248
	v_cndmask_b32_e64 v248, v248, -v248, s[18:19]
	v_fmac_f32_e32 v248, v88, v206
	v_cvt_pk_bf16_f32 v248, v248, s0
	v_mad_i64_i32 v[206:207], s[50:51], v160, s95, v[102:103]
	v_lshl_add_u64 v[206:207], v[206:207], 0, v[100:101]
	global_store_short v[206:207], v248, off
	s_waitcnt vmcnt(15)
	v_mul_f32_e32 v249, v209, v249
	v_cndmask_b32_e64 v249, v249, -v249, s[18:19]
	v_fmac_f32_e32 v249, v89, v208
	v_cvt_pk_bf16_f32 v249, v249, s0
	v_mad_i64_i32 v[208:209], s[50:51], v158, s95, v[102:103]
	v_lshl_add_u64 v[208:209], v[208:209], 0, v[100:101]
	global_store_short v[208:209], v249, off
	s_waitcnt vmcnt(15)
	v_mul_f32_e32 v250, v217, v250
	v_cndmask_b32_e64 v250, v250, -v250, s[18:19]
	v_fmac_f32_e32 v250, v90, v216
	v_cvt_pk_bf16_f32 v250, v250, s0
	v_mad_i64_i32 v[216:217], s[50:51], v156, s95, v[102:103]
	v_lshl_add_u64 v[216:217], v[216:217], 0, v[100:101]
	global_store_short v[216:217], v250, off
	s_waitcnt vmcnt(15)
	v_mul_f32_e32 v251, v219, v251
	v_cndmask_b32_e64 v251, v251, -v251, s[18:19]
	v_fmac_f32_e32 v251, v91, v218
	v_cvt_pk_bf16_f32 v251, v251, s0
	v_mad_i64_i32 v[218:219], s[50:51], v154, s95, v[102:103]
	v_lshl_add_u64 v[218:219], v[218:219], 0, v[100:101]
	global_store_short v[218:219], v251, off
	s_waitcnt vmcnt(15)
	v_mul_f32_e32 v252, v221, v252
	v_cndmask_b32_e64 v252, v252, -v252, s[18:19]
	v_fmac_f32_e32 v252, v92, v220
	v_cvt_pk_bf16_f32 v252, v252, s0
	v_mad_i64_i32 v[220:221], s[50:51], v152, s95, v[102:103]
	v_lshl_add_u64 v[220:221], v[220:221], 0, v[100:101]
	global_store_short v[220:221], v252, off
	s_waitcnt vmcnt(15)
	v_mul_f32_e32 v253, v223, v253
	v_cndmask_b32_e64 v253, v253, -v253, s[18:19]
	v_fmac_f32_e32 v253, v93, v222
	v_cvt_pk_bf16_f32 v253, v253, s0
	v_mad_i64_i32 v[222:223], s[50:51], v150, s95, v[102:103]
	v_lshl_add_u64 v[222:223], v[222:223], 0, v[100:101]
	global_store_short v[222:223], v253, off
	s_waitcnt vmcnt(15)
	v_mul_f32_e32 v254, v225, v254
	v_cndmask_b32_e64 v254, v254, -v254, s[18:19]
	v_fmac_f32_e32 v254, v94, v224
	v_cvt_pk_bf16_f32 v254, v254, s0
	v_mad_i64_i32 v[224:225], s[50:51], v148, s95, v[102:103]
	v_lshl_add_u64 v[224:225], v[224:225], 0, v[100:101]
	global_store_short v[224:225], v254, off
	s_waitcnt vmcnt(15)
	v_mul_f32_e32 v255, v227, v255
	v_cndmask_b32_e64 v255, v255, -v255, s[18:19]
	v_fmac_f32_e32 v255, v95, v226
	v_cvt_pk_bf16_f32 v255, v255, s0
	v_mad_i64_i32 v[226:227], s[50:51], v147, s95, v[102:103]
	v_lshl_add_u64 v[226:227], v[226:227], 0, v[100:101]
	global_store_short v[226:227], v255, off

; DI u16 f2bf(float a) { return (u16)(pk2(a, 0.f) & 0xffffu); }
; DI int crow(int i, int h) { return (i & 3) + 8 * (i >> 2) + 4 * h; }
; template <int EPI>
; __device__ __forceinline__ void gemm_tile(const Params& p, int layer, const u16* __restrict__ A, const u16* __restrict__ Bt, int mt, int nt, char* lds) {
;     ...
;         const bool ropeA = gcb < 1024, ropeB = (gcb >= 1536 && gcb < 2816);
;         const bool latent = m0 >= NCTX;
;         if (latent && (ropeA || ropeB)) {
;           int pair, nf; bool userow; const f32x2* tab;
;           if (ropeA) { pair = (gc & 63) >> 1; nf = 16; tab = (const f32x2*)(p.ws + OFF_TABA); }
;           else       { pair = (gc & 127) >> 1; nf = 32; tab = (const f32x2*)(p.ws + OFF_TABB); }
;           userow = pair < nf;
;           const int f = userow ? pair : pair - nf;
; #pragma unroll
;           for (int e = 0; e < 16; ++e) {
;             const int gr = grb + crow(e, h);
;             const int t = gr - NCTX;
;             const int pos = userow ? (t >> 6) : (t & 63);
;             const f32x2 cs = tab[pos * nf + f];
;             const float v = acc[i][j][e];
;             const float o = __shfl_xor(v, 1);
;             const float res = (gc & 1) ? (o * cs[1] + v * cs[0]) : (v * cs[0] - o * cs[1]);
;             P[(size_t)gr * LDP + gc] = f2bf(res);
;           }
.LBB0_1355:
	s_or_b64 exec, exec, s[10:11]
	v_and_b32_e32 v117, 36, v79
	v_or_b32_e32 v114, 1, v79
	v_or_b32_e32 v110, 2, v79
	v_or_b32_e32 v102, 3, v79
	v_or_b32_e32 v100, 8, v79
	v_or_b32_e32 v98, 9, v79
	v_or_b32_e32 v94, 10, v79
	v_or_b32_e32 v86, 11, v79
	v_or_b32_e32 v84, 16, v79
	v_or_b32_e32 v82, 17, v79
	v_or_b32_e32 v77, 18, v79
	v_or_b32_e32 v75, 19, v79
	v_or_b32_e32 v73, 24, v79
	v_or_b32_e32 v71, 25, v79
	v_or_b32_e32 v69, 26, v79
	v_or_b32_e32 v68, 27, v79
	v_add_u32_e32 v118, 0xffffff20, v130
	v_bitop3_b32 v116, v79, 37, 1 bitop3:0xc8
	v_bitop3_b32 v115, v79, 38, 2 bitop3:0xc8
	v_bitop3_b32 v111, v79, 39, 3 bitop3:0xc8
	v_bitop3_b32 v103, v79, 44, 8 bitop3:0xc8
	v_bitop3_b32 v101, v79, 45, 9 bitop3:0xc8
	s_waitcnt lgkmcnt(0)
	v_bitop3_b32 v99, v79, 46, 10 bitop3:0xc8
	v_bitop3_b32 v95, v79, 47, 11 bitop3:0xc8
	v_bitop3_b32 v87, v79, 52, 16 bitop3:0xc8
	v_bitop3_b32 v85, v79, 53, 17 bitop3:0xc8
	v_bitop3_b32 v83, v79, 54, 18 bitop3:0xc8
	v_bitop3_b32 v78, v79, 55, 19 bitop3:0xc8
	v_bitop3_b32 v76, v79, 60, 24 bitop3:0xc8
	v_bitop3_b32 v74, v79, 61, 25 bitop3:0xc8
	v_bitop3_b32 v72, v79, 62, 26 bitop3:0xc8
	v_bitop3_b32 v70, v79, 63, 27 bitop3:0xc8
	s_and_saveexec_b64 s[14:15], s[20:21]
	s_cbranch_execz .LBB0_1357
	v_lshrrev_b32_e32 v64, 1, v66
	v_and_b32_e32 v67, v64, v144
	v_sub_u32_e32 v81, v67, v143
	v_ashrrev_i32_e32 v97, 6, v118
	v_cmp_lt_u32_e32 vcc, v67, v143
	v_min_u32_e32 v81, v67, v81
	v_lshl_add_u64 v[64:65], s[22:23], 0, v[128:129]
	v_and_b32_e32 v119, 64, v214
	v_xor_b32_e32 v113, 1, v214
	v_add_u32_e32 v119, 64, v119
	v_cmp_lt_i32_e64 s[10:11], v113, v119
	v_ashrrev_i32_e32 v67, 31, v66
	v_and_b32_e32 v128, 1, v66
	v_cndmask_b32_e64 v113, v214, v113, s[10:11]
	v_lshlrev_b32_e32 v113, 2, v113
	v_lshl_add_u64 v[66:67], v[66:67], 1, s[28:29]
	v_cmp_eq_u32_e64 s[10:11], 0, v128
	s_nop 1
	v_cndmask_b32_e32 v190, v117, v97, vcc
	v_lshl_add_u32 v190, v190, v142, v81
	v_ashrrev_i32_e32 v191, 31, v190
	v_lshl_add_u64 v[190:191], v[190:191], 3, v[64:65]
	global_load_dwordx2 v[190:191], v[190:191], off
	ds_bpermute_b32 v240, v113, v48
	v_cndmask_b32_e32 v192, v116, v97, vcc
	v_lshl_add_u32 v192, v192, v142, v81
	v_ashrrev_i32_e32 v193, 31, v192
	v_lshl_add_u64 v[192:193], v[192:193], 3, v[64:65]
	global_load_dwordx2 v[192:193], v[192:193], off
	ds_bpermute_b32 v241, v113, v49
	v_cndmask_b32_e32 v194, v111, v97, vcc
	v_lshl_add_u32 v194, v194, v142, v81
	v_ashrrev_i32_e32 v195, 31, v194
	v_lshl_add_u64 v[194:195], v[194:195], 3, v[64:65]
	global_load_dwordx2 v[194:195], v[194:195], off
	ds_bpermute_b32 v242, v113, v50
	v_cndmask_b32_e32 v196, v115, v97, vcc
	v_lshl_add_u32 v196, v196, v142, v81
	v_ashrrev_i32_e32 v197, 31, v196
	v_lshl_add_u64 v[196:197], v[196:197], 3, v[64:65]
	global_load_dwordx2 v[196:197], v[196:197], off
	ds_bpermute_b32 v243, v113, v51
	v_cndmask_b32_e32 v198, v103, v97, vcc
	v_lshl_add_u32 v198, v198, v142, v81
	v_ashrrev_i32_e32 v199, 31, v198
	v_lshl_add_u64 v[198:199], v[198:199], 3, v[64:65]
	global_load_dwordx2 v[198:199], v[198:199], off
	ds_bpermute_b32 v244, v113, v52
	v_cndmask_b32_e32 v200, v101, v97, vcc
	v_lshl_add_u32 v200, v200, v142, v81
	v_ashrrev_i32_e32 v201, 31, v200
	v_lshl_add_u64 v[200:201], v[200:201], 3, v[64:65]
	global_load_dwordx2 v[200:201], v[200:201], off
	ds_bpermute_b32 v245, v113, v53
	v_cndmask_b32_e32 v202, v99, v97, vcc
	v_lshl_add_u32 v202, v202, v142, v81
	v_ashrrev_i32_e32 v203, 31, v202
	v_lshl_add_u64 v[202:203], v[202:203], 3, v[64:65]
	global_load_dwordx2 v[202:203], v[202:203], off
	ds_bpermute_b32 v246, v113, v54
	v_cndmask_b32_e32 v204, v95, v97, vcc
	v_lshl_add_u32 v204, v204, v142, v81
	v_ashrrev_i32_e32 v205, 31, v204
	v_lshl_add_u64 v[204:205], v[204:205], 3, v[64:65]
	global_load_dwordx2 v[204:205], v[204:205], off
	ds_bpermute_b32 v247, v113, v55
	v_cndmask_b32_e32 v206, v87, v97, vcc
	v_lshl_add_u32 v206, v206, v142, v81
	v_ashrrev_i32_e32 v207, 31, v206
	v_lshl_add_u64 v[206:207], v[206:207], 3, v[64:65]
	global_load_dwordx2 v[206:207], v[206:207], off
	ds_bpermute_b32 v248, v113, v56
	v_cndmask_b32_e32 v208, v85, v97, vcc
	v_lshl_add_u32 v208, v208, v142, v81
	v_ashrrev_i32_e32 v209, 31, v208
	v_lshl_add_u64 v[208:209], v[208:209], 3, v[64:65]
	global_load_dwordx2 v[208:209], v[208:209], off
	ds_bpermute_b32 v249, v113, v57
	v_cndmask_b32_e32 v216, v83, v97, vcc
	v_lshl_add_u32 v216, v216, v142, v81
	v_ashrrev_i32_e32 v217, 31, v216
	v_lshl_add_u64 v[216:217], v[216:217], 3, v[64:65]
	global_load_dwordx2 v[216:217], v[216:217], off
	ds_bpermute_b32 v250, v113, v58
	v_cndmask_b32_e32 v218, v78, v97, vcc
	v_lshl_add_u32 v218, v218, v142, v81
	v_ashrrev_i32_e32 v219, 31, v218
	v_lshl_add_u64 v[218:219], v[218:219], 3, v[64:65]
	global_load_dwordx2 v[218:219], v[218:219], off
	ds_bpermute_b32 v251, v113, v59
	v_cndmask_b32_e32 v220, v76, v97, vcc
	v_lshl_add_u32 v220, v220, v142, v81
	v_ashrrev_i32_e32 v221, 31, v220
	v_lshl_add_u64 v[220:221], v[220:221], 3, v[64:65]
	global_load_dwordx2 v[220:221], v[220:221], off
	ds_bpermute_b32 v252, v113, v60
	v_cndmask_b32_e32 v222, v74, v97, vcc
	v_lshl_add_u32 v222, v222, v142, v81
	v_ashrrev_i32_e32 v223, 31, v222
	v_lshl_add_u64 v[222:223], v[222:223], 3, v[64:65]
	global_load_dwordx2 v[222:223], v[222:223], off
	ds_bpermute_b32 v253, v113, v61
	v_cndmask_b32_e32 v224, v72, v97, vcc
	v_lshl_add_u32 v224, v224, v142, v81
	v_ashrrev_i32_e32 v225, 31, v224
	v_lshl_add_u64 v[224:225], v[224:225], 3, v[64:65]
	global_load_dwordx2 v[224:225], v[224:225], off
	ds_bpermute_b32 v254, v113, v62
	v_cndmask_b32_e32 v226, v70, v97, vcc
	v_lshl_add_u32 v226, v226, v142, v81
	v_ashrrev_i32_e32 v227, 31, v226
	v_lshl_add_u64 v[226:227], v[226:227], 3, v[64:65]
	global_load_dwordx2 v[226:227], v[226:227], off
	ds_bpermute_b32 v255, v113, v63
	s_waitcnt lgkmcnt(0)
; DI u16 f2bf(float a) { return (u16)(pk2(a, 0.f) & 0xffffu); }
; DI int crow(int i, int h) { return (i & 3) + 8 * (i >> 2) + 4 * h; }
; template <int EPI>
; __device__ __forceinline__ void gemm_tile(const Params& p, int layer, const u16* __restrict__ A, const u16* __restrict__ Bt, int mt, int nt, char* lds) {
;     ...
; #pragma unroll
;           for (int e = 0; e < 16; ++e) {
;             const int gr = grb + crow(e, h);
;             const int t = gr - NCTX;
;             const int pos = userow ? (t >> 6) : (t & 63);
;             const f32x2 cs = tab[pos * nf + f];
;             const float v = acc[i][j][e];
;             const float o = __shfl_xor(v, 1);
;             const float res = (gc & 1) ? (o * cs[1] + v * cs[0]) : (v * cs[0] - o * cs[1]);
;             P[(size_t)gr * LDP + gc] = f2bf(res);
;           }
	s_waitcnt vmcnt(15)
	v_mul_f32_e32 v240, v191, v240
	v_cndmask_b32_e64 v240, v240, -v240, s[10:11]
	v_fmac_f32_e32 v240, v48, v190
	v_cvt_pk_bf16_f32 v240, v240, s0
	v_mad_i64_i32 v[190:191], s[20:21], v79, s95, v[66:67]
	global_store_short v[190:191], v240, off
	s_waitcnt vmcnt(15)
	v_mul_f32_e32 v241, v193, v241
	v_cndmask_b32_e64 v241, v241, -v241, s[10:11]
	v_fmac_f32_e32 v241, v49, v192
	v_cvt_pk_bf16_f32 v241, v241, s0
	v_mad_i64_i32 v[192:193], s[20:21], v114, s95, v[66:67]
	global_store_short v[192:193], v241, off
	s_waitcnt vmcnt(15)
	v_mul_f32_e32 v242, v195, v242
	v_cndmask_b32_e64 v242, v242, -v242, s[10:11]
	v_fmac_f32_e32 v242, v50, v194
	v_cvt_pk_bf16_f32 v242, v242, s0
	v_mad_i64_i32 v[194:195], s[20:21], v110, s95, v[66:67]
	global_store_short v[194:195], v242, off
	s_waitcnt vmcnt(15)
	v_mul_f32_e32 v243, v197, v243
	v_cndmask_b32_e64 v243, v243, -v243, s[10:11]
	v_fmac_f32_e32 v243, v51, v196
	v_cvt_pk_bf16_f32 v243, v243, s0
	v_mad_i64_i32 v[196:197], s[20:21], v102, s95, v[66:67]
	global_store_short v[196:197], v243, off
	s_waitcnt vmcnt(15)
	v_mul_f32_e32 v244, v199, v244
	v_cndmask_b32_e64 v244, v244, -v244, s[10:11]
	v_fmac_f32_e32 v244, v52, v198
	v_cvt_pk_bf16_f32 v244, v244, s0
	v_mad_i64_i32 v[198:199], s[20:21], v100, s95, v[66:67]
	global_store_short v[198:199], v244, off
	s_waitcnt vmcnt(15)
	v_mul_f32_e32 v245, v201, v245
	v_cndmask_b32_e64 v245, v245, -v245, s[10:11]
	v_fmac_f32_e32 v245, v53, v200
	v_cvt_pk_bf16_f32 v245, v245, s0
	v_mad_i64_i32 v[200:201], s[20:21], v98, s95, v[66:67]
	global_store_short v[200:201], v245, off
	s_waitcnt vmcnt(15)
	v_mul_f32_e32 v246, v203, v246
	v_cndmask_b32_e64 v246, v246, -v246, s[10:11]
	v_fmac_f32_e32 v246, v54, v202
	v_cvt_pk_bf16_f32 v246, v246, s0
	v_mad_i64_i32 v[202:203], s[20:21], v94, s95, v[66:67]
	global_store_short v[202:203], v246, off
	s_waitcnt vmcnt(15)
	v_mul_f32_e32 v247, v205, v247
	v_cndmask_b32_e64 v247, v247, -v247, s[10:11]
	v_fmac_f32_e32 v247, v55, v204
	v_cvt_pk_bf16_f32 v247, v247, s0
	v_mad_i64_i32 v[204:205], s[20:21], v86, s95, v[66:67]
	global_store_short v[204:205], v247, off
	s_waitcnt vmcnt(15)
	v_mul_f32_e32 v248, v207, v248
	v_cndmask_b32_e64 v248, v248, -v248, s[10:11]
	v_fmac_f32_e32 v248, v56, v206
	v_cvt_pk_bf16_f32 v248, v248, s0
	v_mad_i64_i32 v[206:207], s[20:21], v84, s95, v[66:67]
	global_store_short v[206:207], v248, off
	s_waitcnt vmcnt(15)
	v_mul_f32_e32 v249, v209, v249
	v_cndmask_b32_e64 v249, v249, -v249, s[10:11]
	v_fmac_f32_e32 v249, v57, v208
	v_cvt_pk_bf16_f32 v249, v249, s0
	v_mad_i64_i32 v[208:209], s[20:21], v82, s95, v[66:67]
	global_store_short v[208:209], v249, off
	s_waitcnt vmcnt(15)
	v_mul_f32_e32 v250, v217, v250
	v_cndmask_b32_e64 v250, v250, -v250, s[10:11]
	v_fmac_f32_e32 v250, v58, v216
	v_cvt_pk_bf16_f32 v250, v250, s0
	v_mad_i64_i32 v[216:217], s[20:21], v77, s95, v[66:67]
	global_store_short v[216:217], v250, off
	s_waitcnt vmcnt(15)
	v_mul_f32_e32 v251, v219, v251
	v_cndmask_b32_e64 v251, v251, -v251, s[10:11]
	v_fmac_f32_e32 v251, v59, v218
	v_cvt_pk_bf16_f32 v251, v251, s0
	v_mad_i64_i32 v[218:219], s[20:21], v75, s95, v[66:67]
	global_store_short v[218:219], v251, off
	s_waitcnt vmcnt(15)
	v_mul_f32_e32 v252, v221, v252
	v_cndmask_b32_e64 v252, v252, -v252, s[10:11]
	v_fmac_f32_e32 v252, v60, v220
	v_cvt_pk_bf16_f32 v252, v252, s0
	v_mad_i64_i32 v[220:221], s[20:21], v73, s95, v[66:67]
	global_store_short v[220:221], v252, off
	s_waitcnt vmcnt(15)
	v_mul_f32_e32 v253, v223, v253
	v_cndmask_b32_e64 v253, v253, -v253, s[10:11]
	v_fmac_f32_e32 v253, v61, v222
	v_cvt_pk_bf16_f32 v253, v253, s0
	v_mad_i64_i32 v[222:223], s[20:21], v71, s95, v[66:67]
	global_store_short v[222:223], v253, off
	s_waitcnt vmcnt(15)
	v_mul_f32_e32 v254, v225, v254
	v_cndmask_b32_e64 v254, v254, -v254, s[10:11]
	v_fmac_f32_e32 v254, v62, v224
	v_cvt_pk_bf16_f32 v254, v254, s0
	v_mad_i64_i32 v[224:225], s[20:21], v69, s95, v[66:67]
	global_store_short v[224:225], v254, off
	s_waitcnt vmcnt(15)
	v_mul_f32_e32 v255, v227, v255
	v_cndmask_b32_e64 v255, v255, -v255, s[10:11]
	v_fmac_f32_e32 v255, v63, v226
	v_cvt_pk_bf16_f32 v255, v255, s0
	v_mad_i64_i32 v[226:227], s[20:21], v68, s95, v[66:67]
	global_store_short v[226:227], v255, off

.LBB0_1517:
	s_and_b32 s52, s4, 1
	s_mul_i32 s0, s52, 0x2200
	v_add_u32_e32 v138, s0, v147
	ds_read_b128 v[64:67], v138
	ds_read_b128 v[150:153], v138 offset:32
	s_sub_i32 s0, s49, 32
	s_cmp_gt_u32 s4, 7
	s_cselect_b64 s[10:11], -1, 0
	s_waitcnt lgkmcnt(1)
	v_mfma_f32_32x32x16_bf16 v[64:79], v[64:67], v[80:83], 0
	s_add_i32 s1, s5, 0xfffffee0
	s_ashr_i32 s5, s1, 6
	v_and_or_b32 v149, s0, 32, v133
	s_cmp_lt_u32 s4, 8
	s_waitcnt lgkmcnt(0)
	v_mfma_f32_32x32x16_bf16 v[64:79], v[150:153], v[84:87], v[64:79]
	ds_read_b128 v[150:153], v138 offset:64
	ds_read_b128 v[154:157], v138 offset:96
	s_waitcnt lgkmcnt(1)
	v_mfma_f32_32x32x16_bf16 v[64:79], v[150:153], v[88:91], v[64:79]
	s_waitcnt lgkmcnt(0)
	v_mfma_f32_32x32x16_bf16 v[64:79], v[154:157], v[92:95], v[64:79]
	ds_read_b128 v[150:153], v138 offset:128
	ds_read_b128 v[154:157], v138 offset:160
	s_waitcnt lgkmcnt(1)
	v_mfma_f32_32x32x16_bf16 v[64:79], v[150:153], v[96:99], v[64:79]
	s_waitcnt lgkmcnt(0)
	v_mfma_f32_32x32x16_bf16 v[64:79], v[154:157], v[100:103], v[64:79]
	ds_read_b128 v[150:153], v138 offset:192
	ds_read_b128 v[154:157], v138 offset:224
	v_sub_u32_e32 v138, s5, v144
	v_cmp_gt_u32_e64 s[0:1], 8, v138
	v_sub_u32_e32 v138, s5, v143
	v_mad_u64_u32 v[138:139], s[4:5], v138, 31, v[128:129]
	s_waitcnt lgkmcnt(1)
	v_mfma_f32_32x32x16_bf16 v[64:79], v[150:153], v[104:107], v[64:79]
	s_waitcnt lgkmcnt(0)
	v_mfma_f32_32x32x16_bf16 v[64:79], v[154:157], v[108:111], v[64:79]
	s_cbranch_scc1 .LBB0_1549
	v_mov_b32_e32 v240, v149
	v_sub_u32_e32 v150, v240, v142
	v_cmp_gt_u32_e32 vcc, 16, v150
	v_add_u32_e32 v240, v138, v240
	s_and_b64 vcc, s[0:1], vcc
	v_cndmask_b32_e32 v240, 0, v240, vcc
	v_lshlrev_b32_e32 v240, 2, v240
	ds_read_b32 v240, v240 offset:35840
	v_or_b32_e32 v241, 1, v149
	v_sub_u32_e32 v150, v241, v142
	v_cmp_gt_u32_e32 vcc, 16, v150
	v_add_u32_e32 v241, v138, v241
	s_and_b64 vcc, s[0:1], vcc
	v_cndmask_b32_e32 v241, 0, v241, vcc
	v_lshlrev_b32_e32 v241, 2, v241
	ds_read_b32 v241, v241 offset:35840
	v_or_b32_e32 v242, 2, v149
	v_sub_u32_e32 v150, v242, v142
	v_cmp_gt_u32_e32 vcc, 16, v150
	v_add_u32_e32 v242, v138, v242
	s_and_b64 vcc, s[0:1], vcc
	v_cndmask_b32_e32 v242, 0, v242, vcc
	v_lshlrev_b32_e32 v242, 2, v242
	ds_read_b32 v242, v242 offset:35840
	v_or_b32_e32 v243, 3, v149
	v_sub_u32_e32 v150, v243, v142
	v_cmp_gt_u32_e32 vcc, 16, v150
	v_add_u32_e32 v243, v138, v243
	s_and_b64 vcc, s[0:1], vcc
	v_cndmask_b32_e32 v243, 0, v243, vcc
	v_lshlrev_b32_e32 v243, 2, v243
	ds_read_b32 v243, v243 offset:35840
	v_or_b32_e32 v244, 8, v149
	v_sub_u32_e32 v150, v244, v142
	v_cmp_gt_u32_e32 vcc, 16, v150
	v_add_u32_e32 v244, v138, v244
	s_and_b64 vcc, s[0:1], vcc
	v_cndmask_b32_e32 v244, 0, v244, vcc
	v_lshlrev_b32_e32 v244, 2, v244
	ds_read_b32 v244, v244 offset:35840
	v_or_b32_e32 v245, 9, v149
	v_sub_u32_e32 v150, v245, v142
	v_cmp_gt_u32_e32 vcc, 16, v150
	v_add_u32_e32 v245, v138, v245
	s_and_b64 vcc, s[0:1], vcc
	v_cndmask_b32_e32 v245, 0, v245, vcc
	v_lshlrev_b32_e32 v245, 2, v245
	ds_read_b32 v245, v245 offset:35840
	v_or_b32_e32 v246, 10, v149
	v_sub_u32_e32 v150, v246, v142
	v_cmp_gt_u32_e32 vcc, 16, v150
	v_add_u32_e32 v246, v138, v246
	s_and_b64 vcc, s[0:1], vcc
	v_cndmask_b32_e32 v246, 0, v246, vcc
	v_lshlrev_b32_e32 v246, 2, v246
	ds_read_b32 v246, v246 offset:35840
	v_or_b32_e32 v247, 11, v149
	v_sub_u32_e32 v150, v247, v142
	v_cmp_gt_u32_e32 vcc, 16, v150
	v_add_u32_e32 v247, v138, v247
	s_and_b64 vcc, s[0:1], vcc
	v_cndmask_b32_e32 v247, 0, v247, vcc
	v_lshlrev_b32_e32 v247, 2, v247
	ds_read_b32 v247, v247 offset:35840
	v_or_b32_e32 v248, 16, v149
	v_sub_u32_e32 v150, v248, v142
	v_cmp_gt_u32_e32 vcc, 16, v150
	v_add_u32_e32 v248, v138, v248
	s_and_b64 vcc, s[0:1], vcc
	v_cndmask_b32_e32 v248, 0, v248, vcc
	v_lshlrev_b32_e32 v248, 2, v248
	ds_read_b32 v248, v248 offset:35840
	v_or_b32_e32 v249, 17, v149
	v_sub_u32_e32 v150, v249, v142
	v_cmp_gt_u32_e32 vcc, 16, v150
	v_add_u32_e32 v249, v138, v249
	s_and_b64 vcc, s[0:1], vcc
	v_cndmask_b32_e32 v249, 0, v249, vcc
	v_lshlrev_b32_e32 v249, 2, v249
	ds_read_b32 v249, v249 offset:35840
	v_or_b32_e32 v250, 18, v149
	v_sub_u32_e32 v150, v250, v142
	v_cmp_gt_u32_e32 vcc, 16, v150
	v_add_u32_e32 v250, v138, v250
	s_and_b64 vcc, s[0:1], vcc
	v_cndmask_b32_e32 v250, 0, v250, vcc
	v_lshlrev_b32_e32 v250, 2, v250
	ds_read_b32 v250, v250 offset:35840
	v_or_b32_e32 v251, 19, v149
	v_sub_u32_e32 v150, v251, v142
	v_cmp_gt_u32_e32 vcc, 16, v150
	v_add_u32_e32 v251, v138, v251
	s_and_b64 vcc, s[0:1], vcc
	v_cndmask_b32_e32 v251, 0, v251, vcc
	v_lshlrev_b32_e32 v251, 2, v251
	ds_read_b32 v251, v251 offset:35840
	v_or_b32_e32 v252, 24, v149
	v_sub_u32_e32 v150, v252, v142
	v_cmp_gt_u32_e32 vcc, 16, v150
	v_add_u32_e32 v252, v138, v252
	s_and_b64 vcc, s[0:1], vcc
	v_cndmask_b32_e32 v252, 0, v252, vcc
	v_lshlrev_b32_e32 v252, 2, v252
	ds_read_b32 v252, v252 offset:35840
	v_or_b32_e32 v253, 25, v149
	v_sub_u32_e32 v150, v253, v142
	v_cmp_gt_u32_e32 vcc, 16, v150
	v_add_u32_e32 v253, v138, v253
	s_and_b64 vcc, s[0:1], vcc
	v_cndmask_b32_e32 v253, 0, v253, vcc
	v_lshlrev_b32_e32 v253, 2, v253
	ds_read_b32 v253, v253 offset:35840
	v_or_b32_e32 v254, 26, v149
	v_sub_u32_e32 v150, v254, v142
	v_cmp_gt_u32_e32 vcc, 16, v150
	v_add_u32_e32 v254, v138, v254
	s_and_b64 vcc, s[0:1], vcc
	v_cndmask_b32_e32 v254, 0, v254, vcc
	v_lshlrev_b32_e32 v254, 2, v254
	ds_read_b32 v254, v254 offset:35840
	v_or_b32_e32 v255, 27, v149
	v_sub_u32_e32 v150, v255, v142
	v_cmp_gt_u32_e32 vcc, 16, v150
	v_add_u32_e32 v255, v138, v255
	s_and_b64 vcc, s[0:1], vcc
	v_cndmask_b32_e32 v255, 0, v255, vcc
	v_lshlrev_b32_e32 v255, 2, v255
	ds_read_b32 v255, v255 offset:35840
	s_waitcnt lgkmcnt(0)
	v_mov_b32_e32 v139, v149
	v_sub_u32_e32 v150, v139, v142
	v_cmp_gt_u32_e32 vcc, 16, v150
	v_add_f32_e32 v64, v64, v240
	s_and_b64 vcc, s[0:1], vcc
	v_cndmask_b32_e32 v64, v189, v64, vcc
	v_or_b32_e32 v139, 1, v149
	v_sub_u32_e32 v150, v139, v142
	v_cmp_gt_u32_e32 vcc, 16, v150
	v_add_f32_e32 v65, v65, v241
	s_and_b64 vcc, s[0:1], vcc
	v_cndmask_b32_e32 v65, v189, v65, vcc
	v_or_b32_e32 v139, 2, v149
	v_sub_u32_e32 v150, v139, v142
	v_cmp_gt_u32_e32 vcc, 16, v150
	v_add_f32_e32 v66, v66, v242
	s_and_b64 vcc, s[0:1], vcc
	v_cndmask_b32_e32 v66, v189, v66, vcc
	v_or_b32_e32 v139, 3, v149
	v_sub_u32_e32 v150, v139, v142
	v_cmp_gt_u32_e32 vcc, 16, v150
	v_add_f32_e32 v67, v67, v243
	s_and_b64 vcc, s[0:1], vcc
	v_cndmask_b32_e32 v67, v189, v67, vcc
	v_or_b32_e32 v139, 8, v149
	v_sub_u32_e32 v150, v139, v142
	v_cmp_gt_u32_e32 vcc, 16, v150
	v_add_f32_e32 v68, v68, v244
	s_and_b64 vcc, s[0:1], vcc
	v_cndmask_b32_e32 v68, v189, v68, vcc
	v_or_b32_e32 v139, 9, v149
	v_sub_u32_e32 v150, v139, v142
	v_cmp_gt_u32_e32 vcc, 16, v150
	v_add_f32_e32 v69, v69, v245
	s_and_b64 vcc, s[0:1], vcc
	v_cndmask_b32_e32 v69, v189, v69, vcc
	v_or_b32_e32 v139, 10, v149
	v_sub_u32_e32 v150, v139, v142
	v_cmp_gt_u32_e32 vcc, 16, v150
	v_add_f32_e32 v70, v70, v246
	s_and_b64 vcc, s[0:1], vcc
	v_cndmask_b32_e32 v70, v189, v70, vcc
	v_or_b32_e32 v139, 11, v149
	v_sub_u32_e32 v150, v139, v142
	v_cmp_gt_u32_e32 vcc, 16, v150
	v_add_f32_e32 v71, v71, v247
	s_and_b64 vcc, s[0:1], vcc
	v_cndmask_b32_e32 v71, v189, v71, vcc
	v_or_b32_e32 v139, 16, v149
	v_sub_u32_e32 v150, v139, v142
	v_cmp_gt_u32_e32 vcc, 16, v150
	v_add_f32_e32 v72, v72, v248
	s_and_b64 vcc, s[0:1], vcc
	v_cndmask_b32_e32 v72, v189, v72, vcc
	v_or_b32_e32 v139, 17, v149
	v_sub_u32_e32 v150, v139, v142
	v_cmp_gt_u32_e32 vcc, 16, v150
	v_add_f32_e32 v73, v73, v249
	s_and_b64 vcc, s[0:1], vcc
	v_cndmask_b32_e32 v73, v189, v73, vcc
	v_or_b32_e32 v139, 18, v149
	v_sub_u32_e32 v150, v139, v142
	v_cmp_gt_u32_e32 vcc, 16, v150
	v_add_f32_e32 v74, v74, v250
	s_and_b64 vcc, s[0:1], vcc
	v_cndmask_b32_e32 v74, v189, v74, vcc
	v_or_b32_e32 v139, 19, v149
	v_sub_u32_e32 v150, v139, v142
	v_cmp_gt_u32_e32 vcc, 16, v150
	v_add_f32_e32 v75, v75, v251
	s_and_b64 vcc, s[0:1], vcc
	v_cndmask_b32_e32 v75, v189, v75, vcc
	v_or_b32_e32 v139, 24, v149
	v_sub_u32_e32 v150, v139, v142
	v_cmp_gt_u32_e32 vcc, 16, v150
	v_add_f32_e32 v76, v76, v252
	s_and_b64 vcc, s[0:1], vcc
	v_cndmask_b32_e32 v76, v189, v76, vcc
	v_or_b32_e32 v139, 25, v149
	v_sub_u32_e32 v150, v139, v142
	v_cmp_gt_u32_e32 vcc, 16, v150
	v_add_f32_e32 v77, v77, v253
	s_and_b64 vcc, s[0:1], vcc
	v_cndmask_b32_e32 v77, v189, v77, vcc
	v_or_b32_e32 v139, 26, v149
	v_sub_u32_e32 v150, v139, v142
	v_cmp_gt_u32_e32 vcc, 16, v150
	v_add_f32_e32 v78, v78, v254
	s_and_b64 vcc, s[0:1], vcc
	v_cndmask_b32_e32 v78, v189, v78, vcc
	v_or_b32_e32 v139, 27, v149
	v_sub_u32_e32 v150, v139, v142
	v_cmp_gt_u32_e32 vcc, 16, v150
	v_add_f32_e32 v79, v79, v255
	s_and_b64 vcc, s[0:1], vcc
	v_cndmask_b32_e32 v79, v189, v79, vcc

; DI u16 f2bf(float a) { return (u16)(pk2(a, 0.f) & 0xffffu); }
; DI int crow(int i, int h) { return (i & 3) + 8 * (i >> 2) + 4 * h; }
; template <int EPI>
; __device__ __forceinline__ void gemm_tile(const Params& p, int layer, const u16* __restrict__ A, const u16* __restrict__ Bt, int mt, int nt, char* lds) {
;     ...
;         const bool ropeA = gcb < 1024, ropeB = (gcb >= 1536 && gcb < 2816);
;         const bool latent = m0 >= NCTX;
;         if (latent && (ropeA || ropeB)) {
;           int pair, nf; bool userow; const f32x2* tab;
;           if (ropeA) { pair = (gc & 63) >> 1; nf = 16; tab = (const f32x2*)(p.ws + OFF_TABA); }
;           else       { pair = (gc & 127) >> 1; nf = 32; tab = (const f32x2*)(p.ws + OFF_TABB); }
;           userow = pair < nf;
;           const int f = userow ? pair : pair - nf;
; #pragma unroll
;           for (int e = 0; e < 16; ++e) {
;             const int gr = grb + crow(e, h);
;             const int t = gr - NCTX;
;             const int pos = userow ? (t >> 6) : (t & 63);
;             const f32x2 cs = tab[pos * nf + f];
;             const float v = acc[i][j][e];
;             const float o = __shfl_xor(v, 1);
;             const float res = (gc & 1) ? (o * cs[1] + v * cs[0]) : (v * cs[0] - o * cs[1]);
;             P[(size_t)gr * LDP + gc] = f2bf(res);
;           }
.LBB0_2119:
	s_or_b64 exec, exec, s[6:7]
	v_and_b32_e32 v117, 36, v79
	v_or_b32_e32 v114, 1, v79
	v_or_b32_e32 v110, 2, v79
	v_or_b32_e32 v102, 3, v79
	v_or_b32_e32 v100, 8, v79
	v_or_b32_e32 v98, 9, v79
	v_or_b32_e32 v94, 10, v79
	v_or_b32_e32 v86, 11, v79
	v_or_b32_e32 v84, 16, v79
	v_or_b32_e32 v82, 17, v79
	v_or_b32_e32 v77, 18, v79
	v_or_b32_e32 v75, 19, v79
	v_or_b32_e32 v73, 24, v79
	v_or_b32_e32 v71, 25, v79
	v_or_b32_e32 v69, 26, v79
	v_or_b32_e32 v68, 27, v79
	v_add_u32_e32 v118, 0xffffff20, v130
	v_bitop3_b32 v116, v79, 37, 1 bitop3:0xc8
	v_bitop3_b32 v115, v79, 38, 2 bitop3:0xc8
	v_bitop3_b32 v111, v79, 39, 3 bitop3:0xc8
	v_bitop3_b32 v103, v79, 44, 8 bitop3:0xc8
	v_bitop3_b32 v101, v79, 45, 9 bitop3:0xc8
	s_waitcnt lgkmcnt(0)
	v_bitop3_b32 v99, v79, 46, 10 bitop3:0xc8
	v_bitop3_b32 v95, v79, 47, 11 bitop3:0xc8
	v_bitop3_b32 v87, v79, 52, 16 bitop3:0xc8
	v_bitop3_b32 v85, v79, 53, 17 bitop3:0xc8
	v_bitop3_b32 v83, v79, 54, 18 bitop3:0xc8
	v_bitop3_b32 v78, v79, 55, 19 bitop3:0xc8
	v_bitop3_b32 v76, v79, 60, 24 bitop3:0xc8
	v_bitop3_b32 v74, v79, 61, 25 bitop3:0xc8
	v_bitop3_b32 v72, v79, 62, 26 bitop3:0xc8
	v_bitop3_b32 v70, v79, 63, 27 bitop3:0xc8
	s_and_saveexec_b64 s[10:11], s[20:21]
	s_cbranch_execz .LBB0_2121
	v_lshrrev_b32_e32 v64, 1, v66
	v_and_b32_e32 v67, v64, v144
	v_sub_u32_e32 v81, v67, v143
	v_ashrrev_i32_e32 v97, 6, v118
	v_cmp_lt_u32_e32 vcc, v67, v143
	v_min_u32_e32 v81, v67, v81
	v_lshl_add_u64 v[64:65], s[22:23], 0, v[128:129]
	v_and_b32_e32 v119, 64, v214
	v_xor_b32_e32 v113, 1, v214
	v_add_u32_e32 v119, 64, v119
	v_cmp_lt_i32_e64 s[6:7], v113, v119
	v_ashrrev_i32_e32 v67, 31, v66
	v_and_b32_e32 v128, 1, v66
	v_cndmask_b32_e64 v113, v214, v113, s[6:7]
	v_lshlrev_b32_e32 v113, 2, v113
	v_lshl_add_u64 v[66:67], v[66:67], 1, s[28:29]
	v_cmp_eq_u32_e64 s[6:7], 0, v128
	s_nop 1
	v_cndmask_b32_e32 v190, v117, v97, vcc
	v_lshl_add_u32 v190, v190, v142, v81
	v_ashrrev_i32_e32 v191, 31, v190
	v_lshl_add_u64 v[190:191], v[190:191], 3, v[64:65]
	global_load_dwordx2 v[190:191], v[190:191], off
	ds_bpermute_b32 v240, v113, v48
	v_cndmask_b32_e32 v192, v116, v97, vcc
	v_lshl_add_u32 v192, v192, v142, v81
	v_ashrrev_i32_e32 v193, 31, v192
	v_lshl_add_u64 v[192:193], v[192:193], 3, v[64:65]
	global_load_dwordx2 v[192:193], v[192:193], off
	ds_bpermute_b32 v241, v113, v49
	v_cndmask_b32_e32 v194, v111, v97, vcc
	v_lshl_add_u32 v194, v194, v142, v81
	v_ashrrev_i32_e32 v195, 31, v194
	v_lshl_add_u64 v[194:195], v[194:195], 3, v[64:65]
	global_load_dwordx2 v[194:195], v[194:195], off
	ds_bpermute_b32 v242, v113, v50
	v_cndmask_b32_e32 v196, v115, v97, vcc
	v_lshl_add_u32 v196, v196, v142, v81
	v_ashrrev_i32_e32 v197, 31, v196
	v_lshl_add_u64 v[196:197], v[196:197], 3, v[64:65]
	global_load_dwordx2 v[196:197], v[196:197], off
	ds_bpermute_b32 v243, v113, v51
	v_cndmask_b32_e32 v198, v103, v97, vcc
	v_lshl_add_u32 v198, v198, v142, v81
	v_ashrrev_i32_e32 v199, 31, v198
	v_lshl_add_u64 v[198:199], v[198:199], 3, v[64:65]
	global_load_dwordx2 v[198:199], v[198:199], off
	ds_bpermute_b32 v244, v113, v52
	v_cndmask_b32_e32 v200, v101, v97, vcc
	v_lshl_add_u32 v200, v200, v142, v81
	v_ashrrev_i32_e32 v201, 31, v200
	v_lshl_add_u64 v[200:201], v[200:201], 3, v[64:65]
	global_load_dwordx2 v[200:201], v[200:201], off
	ds_bpermute_b32 v245, v113, v53
	v_cndmask_b32_e32 v202, v99, v97, vcc
	v_lshl_add_u32 v202, v202, v142, v81
	v_ashrrev_i32_e32 v203, 31, v202
	v_lshl_add_u64 v[202:203], v[202:203], 3, v[64:65]
	global_load_dwordx2 v[202:203], v[202:203], off
	ds_bpermute_b32 v246, v113, v54
	v_cndmask_b32_e32 v204, v95, v97, vcc
	v_lshl_add_u32 v204, v204, v142, v81
	v_ashrrev_i32_e32 v205, 31, v204
	v_lshl_add_u64 v[204:205], v[204:205], 3, v[64:65]
	global_load_dwordx2 v[204:205], v[204:205], off
	ds_bpermute_b32 v247, v113, v55
	v_cndmask_b32_e32 v206, v87, v97, vcc
	v_lshl_add_u32 v206, v206, v142, v81
	v_ashrrev_i32_e32 v207, 31, v206
	v_lshl_add_u64 v[206:207], v[206:207], 3, v[64:65]
	global_load_dwordx2 v[206:207], v[206:207], off
	ds_bpermute_b32 v248, v113, v56
	v_cndmask_b32_e32 v208, v85, v97, vcc
	v_lshl_add_u32 v208, v208, v142, v81
	v_ashrrev_i32_e32 v209, 31, v208
	v_lshl_add_u64 v[208:209], v[208:209], 3, v[64:65]
	global_load_dwordx2 v[208:209], v[208:209], off
	ds_bpermute_b32 v249, v113, v57
	v_cndmask_b32_e32 v216, v83, v97, vcc
	v_lshl_add_u32 v216, v216, v142, v81
	v_ashrrev_i32_e32 v217, 31, v216
	v_lshl_add_u64 v[216:217], v[216:217], 3, v[64:65]
	global_load_dwordx2 v[216:217], v[216:217], off
	ds_bpermute_b32 v250, v113, v58
	v_cndmask_b32_e32 v218, v78, v97, vcc
	v_lshl_add_u32 v218, v218, v142, v81
	v_ashrrev_i32_e32 v219, 31, v218
	v_lshl_add_u64 v[218:219], v[218:219], 3, v[64:65]
	global_load_dwordx2 v[218:219], v[218:219], off
	ds_bpermute_b32 v251, v113, v59
	v_cndmask_b32_e32 v220, v76, v97, vcc
	v_lshl_add_u32 v220, v220, v142, v81
	v_ashrrev_i32_e32 v221, 31, v220
	v_lshl_add_u64 v[220:221], v[220:221], 3, v[64:65]
	global_load_dwordx2 v[220:221], v[220:221], off
	ds_bpermute_b32 v252, v113, v60
	v_cndmask_b32_e32 v222, v74, v97, vcc
	v_lshl_add_u32 v222, v222, v142, v81
	v_ashrrev_i32_e32 v223, 31, v222
	v_lshl_add_u64 v[222:223], v[222:223], 3, v[64:65]
	global_load_dwordx2 v[222:223], v[222:223], off
	ds_bpermute_b32 v253, v113, v61
	v_cndmask_b32_e32 v224, v72, v97, vcc
	v_lshl_add_u32 v224, v224, v142, v81
	v_ashrrev_i32_e32 v225, 31, v224
	v_lshl_add_u64 v[224:225], v[224:225], 3, v[64:65]
	global_load_dwordx2 v[224:225], v[224:225], off
	ds_bpermute_b32 v254, v113, v62
	v_cndmask_b32_e32 v226, v70, v97, vcc
	v_lshl_add_u32 v226, v226, v142, v81
	v_ashrrev_i32_e32 v227, 31, v226
	v_lshl_add_u64 v[226:227], v[226:227], 3, v[64:65]
	global_load_dwordx2 v[226:227], v[226:227], off
	ds_bpermute_b32 v255, v113, v63
	s_waitcnt lgkmcnt(0)
; DI u16 f2bf(float a) { return (u16)(pk2(a, 0.f) & 0xffffu); }
; DI int crow(int i, int h) { return (i & 3) + 8 * (i >> 2) + 4 * h; }
; template <int EPI>
; __device__ __forceinline__ void gemm_tile(const Params& p, int layer, const u16* __restrict__ A, const u16* __restrict__ Bt, int mt, int nt, char* lds) {
;     ...
; #pragma unroll
;           for (int e = 0; e < 16; ++e) {
;             const int gr = grb + crow(e, h);
;             const int t = gr - NCTX;
;             const int pos = userow ? (t >> 6) : (t & 63);
;             const f32x2 cs = tab[pos * nf + f];
;             const float v = acc[i][j][e];
;             const float o = __shfl_xor(v, 1);
;             const float res = (gc & 1) ? (o * cs[1] + v * cs[0]) : (v * cs[0] - o * cs[1]);
;             P[(size_t)gr * LDP + gc] = f2bf(res);
;           }
	s_waitcnt vmcnt(15)
	v_mul_f32_e32 v240, v191, v240
	v_cndmask_b32_e64 v240, v240, -v240, s[6:7]
	v_fmac_f32_e32 v240, v48, v190
	v_cvt_pk_bf16_f32 v240, v240, s0
	v_mad_i64_i32 v[190:191], s[20:21], v79, s90, v[66:67]
	global_store_short v[190:191], v240, off
	s_waitcnt vmcnt(15)
	v_mul_f32_e32 v241, v193, v241
	v_cndmask_b32_e64 v241, v241, -v241, s[6:7]
	v_fmac_f32_e32 v241, v49, v192
	v_cvt_pk_bf16_f32 v241, v241, s0
	v_mad_i64_i32 v[192:193], s[20:21], v114, s90, v[66:67]
	global_store_short v[192:193], v241, off
	s_waitcnt vmcnt(15)
	v_mul_f32_e32 v242, v195, v242
	v_cndmask_b32_e64 v242, v242, -v242, s[6:7]
	v_fmac_f32_e32 v242, v50, v194
	v_cvt_pk_bf16_f32 v242, v242, s0
	v_mad_i64_i32 v[194:195], s[20:21], v110, s90, v[66:67]
	global_store_short v[194:195], v242, off
	s_waitcnt vmcnt(15)
	v_mul_f32_e32 v243, v197, v243
	v_cndmask_b32_e64 v243, v243, -v243, s[6:7]
	v_fmac_f32_e32 v243, v51, v196
	v_cvt_pk_bf16_f32 v243, v243, s0
	v_mad_i64_i32 v[196:197], s[20:21], v102, s90, v[66:67]
	global_store_short v[196:197], v243, off
	s_waitcnt vmcnt(15)
	v_mul_f32_e32 v244, v199, v244
	v_cndmask_b32_e64 v244, v244, -v244, s[6:7]
	v_fmac_f32_e32 v244, v52, v198
	v_cvt_pk_bf16_f32 v244, v244, s0
	v_mad_i64_i32 v[198:199], s[20:21], v100, s90, v[66:67]
	global_store_short v[198:199], v244, off
	s_waitcnt vmcnt(15)
	v_mul_f32_e32 v245, v201, v245
	v_cndmask_b32_e64 v245, v245, -v245, s[6:7]
	v_fmac_f32_e32 v245, v53, v200
	v_cvt_pk_bf16_f32 v245, v245, s0
	v_mad_i64_i32 v[200:201], s[20:21], v98, s90, v[66:67]
	global_store_short v[200:201], v245, off
	s_waitcnt vmcnt(15)
	v_mul_f32_e32 v246, v203, v246
	v_cndmask_b32_e64 v246, v246, -v246, s[6:7]
	v_fmac_f32_e32 v246, v54, v202
	v_cvt_pk_bf16_f32 v246, v246, s0
	v_mad_i64_i32 v[202:203], s[20:21], v94, s90, v[66:67]
	global_store_short v[202:203], v246, off
	s_waitcnt vmcnt(15)
	v_mul_f32_e32 v247, v205, v247
	v_cndmask_b32_e64 v247, v247, -v247, s[6:7]
	v_fmac_f32_e32 v247, v55, v204
	v_cvt_pk_bf16_f32 v247, v247, s0
	v_mad_i64_i32 v[204:205], s[20:21], v86, s90, v[66:67]
	global_store_short v[204:205], v247, off
	s_waitcnt vmcnt(15)
	v_mul_f32_e32 v248, v207, v248
	v_cndmask_b32_e64 v248, v248, -v248, s[6:7]
	v_fmac_f32_e32 v248, v56, v206
	v_cvt_pk_bf16_f32 v248, v248, s0
	v_mad_i64_i32 v[206:207], s[20:21], v84, s90, v[66:67]
	global_store_short v[206:207], v248, off
	s_waitcnt vmcnt(15)
	v_mul_f32_e32 v249, v209, v249
	v_cndmask_b32_e64 v249, v249, -v249, s[6:7]
	v_fmac_f32_e32 v249, v57, v208
	v_cvt_pk_bf16_f32 v249, v249, s0
	v_mad_i64_i32 v[208:209], s[20:21], v82, s90, v[66:67]
	global_store_short v[208:209], v249, off
	s_waitcnt vmcnt(15)
	v_mul_f32_e32 v250, v217, v250
	v_cndmask_b32_e64 v250, v250, -v250, s[6:7]
	v_fmac_f32_e32 v250, v58, v216
	v_cvt_pk_bf16_f32 v250, v250, s0
	v_mad_i64_i32 v[216:217], s[20:21], v77, s90, v[66:67]
	global_store_short v[216:217], v250, off
	s_waitcnt vmcnt(15)
	v_mul_f32_e32 v251, v219, v251
	v_cndmask_b32_e64 v251, v251, -v251, s[6:7]
	v_fmac_f32_e32 v251, v59, v218
	v_cvt_pk_bf16_f32 v251, v251, s0
	v_mad_i64_i32 v[218:219], s[20:21], v75, s90, v[66:67]
	global_store_short v[218:219], v251, off
	s_waitcnt vmcnt(15)
	v_mul_f32_e32 v252, v221, v252
	v_cndmask_b32_e64 v252, v252, -v252, s[6:7]
	v_fmac_f32_e32 v252, v60, v220
	v_cvt_pk_bf16_f32 v252, v252, s0
	v_mad_i64_i32 v[220:221], s[20:21], v73, s90, v[66:67]
	global_store_short v[220:221], v252, off
	s_waitcnt vmcnt(15)
	v_mul_f32_e32 v253, v223, v253
	v_cndmask_b32_e64 v253, v253, -v253, s[6:7]
	v_fmac_f32_e32 v253, v61, v222
	v_cvt_pk_bf16_f32 v253, v253, s0
	v_mad_i64_i32 v[222:223], s[20:21], v71, s90, v[66:67]
	global_store_short v[222:223], v253, off
	s_waitcnt vmcnt(15)
	v_mul_f32_e32 v254, v225, v254
	v_cndmask_b32_e64 v254, v254, -v254, s[6:7]
	v_fmac_f32_e32 v254, v62, v224
	v_cvt_pk_bf16_f32 v254, v254, s0
	v_mad_i64_i32 v[224:225], s[20:21], v69, s90, v[66:67]
	global_store_short v[224:225], v254, off
	s_waitcnt vmcnt(15)
	v_mul_f32_e32 v255, v227, v255
	v_cndmask_b32_e64 v255, v255, -v255, s[6:7]
	v_fmac_f32_e32 v255, v63, v226
	v_cvt_pk_bf16_f32 v255, v255, s0
	v_mad_i64_i32 v[226:227], s[20:21], v68, s90, v[66:67]
	global_store_short v[226:227], v255, off

.LBB0_2273:
	s_and_b32 s52, s4, 1
	s_mul_i32 s0, s52, 0x2200
	v_add_u32_e32 v147, s0, v145
	ds_read_b128 v[64:67], v147
	ds_read_b128 v[148:151], v147 offset:32
	s_sub_i32 s0, s12, 32
	s_cmp_gt_u32 s4, 7
	s_cselect_b64 s[8:9], -1, 0
	s_waitcnt lgkmcnt(1)
	v_mfma_f32_32x32x16_bf16 v[64:79], v[64:67], v[80:83], 0
	s_add_i32 s1, s5, 0xfffffee0
	s_ashr_i32 s5, s1, 6
	s_cmp_lt_u32 s4, 8
	s_waitcnt lgkmcnt(0)
	v_mfma_f32_32x32x16_bf16 v[64:79], v[148:151], v[84:87], v[64:79]
	ds_read_b128 v[148:151], v147 offset:64
	ds_read_b128 v[152:155], v147 offset:96
	s_waitcnt lgkmcnt(1)
	v_mfma_f32_32x32x16_bf16 v[64:79], v[148:151], v[88:91], v[64:79]
	s_waitcnt lgkmcnt(0)
	v_mfma_f32_32x32x16_bf16 v[64:79], v[152:155], v[92:95], v[64:79]
	ds_read_b128 v[148:151], v147 offset:128
	ds_read_b128 v[152:155], v147 offset:160
	s_waitcnt lgkmcnt(1)
	v_mfma_f32_32x32x16_bf16 v[64:79], v[148:151], v[96:99], v[64:79]
	s_waitcnt lgkmcnt(0)
	v_mfma_f32_32x32x16_bf16 v[64:79], v[152:155], v[100:103], v[64:79]
	ds_read_b128 v[148:151], v147 offset:192
	ds_read_b128 v[152:155], v147 offset:224
	v_and_or_b32 v147, s0, 32, v131
	s_waitcnt lgkmcnt(1)
	v_mfma_f32_32x32x16_bf16 v[64:79], v[148:151], v[104:107], v[64:79]
	v_sub_u32_e32 v148, s5, v142
	v_cmp_gt_u32_e64 s[0:1], 8, v148
	v_sub_u32_e32 v148, s5, v140
	v_mul_lo_u32 v148, v148, 31
	v_sub_u32_e32 v148, v148, v141
	v_add_u32_e32 v148, 0xe8, v148
	s_waitcnt lgkmcnt(0)
	v_mfma_f32_32x32x16_bf16 v[64:79], v[152:155], v[108:111], v[64:79]
	s_cbranch_scc1 .LBB0_2305
	v_mov_b32_e32 v240, v147
	v_sub_u32_e32 v150, v240, v143
	v_cmp_gt_u32_e32 vcc, 16, v150
	v_add_u32_e32 v240, v148, v240
	s_and_b64 vcc, s[0:1], vcc
	v_cndmask_b32_e32 v240, 0, v240, vcc
	v_lshlrev_b32_e32 v240, 2, v240
	ds_read_b32 v240, v240 offset:35840
	v_or_b32_e32 v241, 1, v147
	v_sub_u32_e32 v150, v241, v143
	v_cmp_gt_u32_e32 vcc, 16, v150
	v_add_u32_e32 v241, v148, v241
	s_and_b64 vcc, s[0:1], vcc
	v_cndmask_b32_e32 v241, 0, v241, vcc
	v_lshlrev_b32_e32 v241, 2, v241
	ds_read_b32 v241, v241 offset:35840
	v_or_b32_e32 v242, 2, v147
	v_sub_u32_e32 v150, v242, v143
	v_cmp_gt_u32_e32 vcc, 16, v150
	v_add_u32_e32 v242, v148, v242
	s_and_b64 vcc, s[0:1], vcc
	v_cndmask_b32_e32 v242, 0, v242, vcc
	v_lshlrev_b32_e32 v242, 2, v242
	ds_read_b32 v242, v242 offset:35840
	v_or_b32_e32 v243, 3, v147
	v_sub_u32_e32 v150, v243, v143
	v_cmp_gt_u32_e32 vcc, 16, v150
	v_add_u32_e32 v243, v148, v243
	s_and_b64 vcc, s[0:1], vcc
	v_cndmask_b32_e32 v243, 0, v243, vcc
	v_lshlrev_b32_e32 v243, 2, v243
	ds_read_b32 v243, v243 offset:35840
	v_or_b32_e32 v244, 8, v147
	v_sub_u32_e32 v150, v244, v143
	v_cmp_gt_u32_e32 vcc, 16, v150
	v_add_u32_e32 v244, v148, v244
	s_and_b64 vcc, s[0:1], vcc
	v_cndmask_b32_e32 v244, 0, v244, vcc
	v_lshlrev_b32_e32 v244, 2, v244
	ds_read_b32 v244, v244 offset:35840
	v_or_b32_e32 v245, 9, v147
	v_sub_u32_e32 v150, v245, v143
	v_cmp_gt_u32_e32 vcc, 16, v150
	v_add_u32_e32 v245, v148, v245
	s_and_b64 vcc, s[0:1], vcc
	v_cndmask_b32_e32 v245, 0, v245, vcc
	v_lshlrev_b32_e32 v245, 2, v245
	ds_read_b32 v245, v245 offset:35840
	v_or_b32_e32 v246, 10, v147
	v_sub_u32_e32 v150, v246, v143
	v_cmp_gt_u32_e32 vcc, 16, v150
	v_add_u32_e32 v246, v148, v246
	s_and_b64 vcc, s[0:1], vcc
	v_cndmask_b32_e32 v246, 0, v246, vcc
	v_lshlrev_b32_e32 v246, 2, v246
	ds_read_b32 v246, v246 offset:35840
	v_or_b32_e32 v247, 11, v147
	v_sub_u32_e32 v150, v247, v143
	v_cmp_gt_u32_e32 vcc, 16, v150
	v_add_u32_e32 v247, v148, v247
	s_and_b64 vcc, s[0:1], vcc
	v_cndmask_b32_e32 v247, 0, v247, vcc
	v_lshlrev_b32_e32 v247, 2, v247
	ds_read_b32 v247, v247 offset:35840
	v_or_b32_e32 v248, 16, v147
	v_sub_u32_e32 v150, v248, v143
	v_cmp_gt_u32_e32 vcc, 16, v150
	v_add_u32_e32 v248, v148, v248
	s_and_b64 vcc, s[0:1], vcc
	v_cndmask_b32_e32 v248, 0, v248, vcc
	v_lshlrev_b32_e32 v248, 2, v248
	ds_read_b32 v248, v248 offset:35840
	v_or_b32_e32 v249, 17, v147
	v_sub_u32_e32 v150, v249, v143
	v_cmp_gt_u32_e32 vcc, 16, v150
	v_add_u32_e32 v249, v148, v249
	s_and_b64 vcc, s[0:1], vcc
	v_cndmask_b32_e32 v249, 0, v249, vcc
	v_lshlrev_b32_e32 v249, 2, v249
	ds_read_b32 v249, v249 offset:35840
	v_or_b32_e32 v250, 18, v147
	v_sub_u32_e32 v150, v250, v143
	v_cmp_gt_u32_e32 vcc, 16, v150
	v_add_u32_e32 v250, v148, v250
	s_and_b64 vcc, s[0:1], vcc
	v_cndmask_b32_e32 v250, 0, v250, vcc
	v_lshlrev_b32_e32 v250, 2, v250
	ds_read_b32 v250, v250 offset:35840
	v_or_b32_e32 v251, 19, v147
	v_sub_u32_e32 v150, v251, v143
	v_cmp_gt_u32_e32 vcc, 16, v150
	v_add_u32_e32 v251, v148, v251
	s_and_b64 vcc, s[0:1], vcc
	v_cndmask_b32_e32 v251, 0, v251, vcc
	v_lshlrev_b32_e32 v251, 2, v251
	ds_read_b32 v251, v251 offset:35840
	v_or_b32_e32 v252, 24, v147
	v_sub_u32_e32 v150, v252, v143
	v_cmp_gt_u32_e32 vcc, 16, v150
	v_add_u32_e32 v252, v148, v252
	s_and_b64 vcc, s[0:1], vcc
	v_cndmask_b32_e32 v252, 0, v252, vcc
	v_lshlrev_b32_e32 v252, 2, v252
	ds_read_b32 v252, v252 offset:35840
	v_or_b32_e32 v253, 25, v147
	v_sub_u32_e32 v150, v253, v143
	v_cmp_gt_u32_e32 vcc, 16, v150
	v_add_u32_e32 v253, v148, v253
	s_and_b64 vcc, s[0:1], vcc
	v_cndmask_b32_e32 v253, 0, v253, vcc
	v_lshlrev_b32_e32 v253, 2, v253
	ds_read_b32 v253, v253 offset:35840
	v_or_b32_e32 v254, 26, v147
	v_sub_u32_e32 v150, v254, v143
	v_cmp_gt_u32_e32 vcc, 16, v150
	v_add_u32_e32 v254, v148, v254
	s_and_b64 vcc, s[0:1], vcc
	v_cndmask_b32_e32 v254, 0, v254, vcc
	v_lshlrev_b32_e32 v254, 2, v254
	ds_read_b32 v254, v254 offset:35840
	v_or_b32_e32 v255, 27, v147
	v_sub_u32_e32 v150, v255, v143
	v_cmp_gt_u32_e32 vcc, 16, v150
	v_add_u32_e32 v255, v148, v255
	s_and_b64 vcc, s[0:1], vcc
	v_cndmask_b32_e32 v255, 0, v255, vcc
	v_lshlrev_b32_e32 v255, 2, v255
	ds_read_b32 v255, v255 offset:35840
	s_waitcnt lgkmcnt(0)
	v_mov_b32_e32 v149, v147
	v_sub_u32_e32 v150, v149, v143
	v_cmp_gt_u32_e32 vcc, 16, v150
	v_add_f32_e32 v64, v64, v240
	s_and_b64 vcc, s[0:1], vcc
	v_cndmask_b32_e32 v64, v188, v64, vcc
	v_or_b32_e32 v149, 1, v147
	v_sub_u32_e32 v150, v149, v143
	v_cmp_gt_u32_e32 vcc, 16, v150
	v_add_f32_e32 v65, v65, v241
	s_and_b64 vcc, s[0:1], vcc
	v_cndmask_b32_e32 v65, v188, v65, vcc
	v_or_b32_e32 v149, 2, v147
	v_sub_u32_e32 v150, v149, v143
	v_cmp_gt_u32_e32 vcc, 16, v150
	v_add_f32_e32 v66, v66, v242
	s_and_b64 vcc, s[0:1], vcc
	v_cndmask_b32_e32 v66, v188, v66, vcc
	v_or_b32_e32 v149, 3, v147
	v_sub_u32_e32 v150, v149, v143
	v_cmp_gt_u32_e32 vcc, 16, v150
	v_add_f32_e32 v67, v67, v243
	s_and_b64 vcc, s[0:1], vcc
	v_cndmask_b32_e32 v67, v188, v67, vcc
	v_or_b32_e32 v149, 8, v147
	v_sub_u32_e32 v150, v149, v143
	v_cmp_gt_u32_e32 vcc, 16, v150
	v_add_f32_e32 v68, v68, v244
	s_and_b64 vcc, s[0:1], vcc
	v_cndmask_b32_e32 v68, v188, v68, vcc
	v_or_b32_e32 v149, 9, v147
	v_sub_u32_e32 v150, v149, v143
	v_cmp_gt_u32_e32 vcc, 16, v150
	v_add_f32_e32 v69, v69, v245
	s_and_b64 vcc, s[0:1], vcc
	v_cndmask_b32_e32 v69, v188, v69, vcc
	v_or_b32_e32 v149, 10, v147
	v_sub_u32_e32 v150, v149, v143
	v_cmp_gt_u32_e32 vcc, 16, v150
	v_add_f32_e32 v70, v70, v246
	s_and_b64 vcc, s[0:1], vcc
	v_cndmask_b32_e32 v70, v188, v70, vcc
	v_or_b32_e32 v149, 11, v147
	v_sub_u32_e32 v150, v149, v143
	v_cmp_gt_u32_e32 vcc, 16, v150
	v_add_f32_e32 v71, v71, v247
	s_and_b64 vcc, s[0:1], vcc
	v_cndmask_b32_e32 v71, v188, v71, vcc
	v_or_b32_e32 v149, 16, v147
	v_sub_u32_e32 v150, v149, v143
	v_cmp_gt_u32_e32 vcc, 16, v150
	v_add_f32_e32 v72, v72, v248
	s_and_b64 vcc, s[0:1], vcc
	v_cndmask_b32_e32 v72, v188, v72, vcc
	v_or_b32_e32 v149, 17, v147
	v_sub_u32_e32 v150, v149, v143
	v_cmp_gt_u32_e32 vcc, 16, v150
	v_add_f32_e32 v73, v73, v249
	s_and_b64 vcc, s[0:1], vcc
	v_cndmask_b32_e32 v73, v188, v73, vcc
	v_or_b32_e32 v149, 18, v147
	v_sub_u32_e32 v150, v149, v143
	v_cmp_gt_u32_e32 vcc, 16, v150
	v_add_f32_e32 v74, v74, v250
	s_and_b64 vcc, s[0:1], vcc
	v_cndmask_b32_e32 v74, v188, v74, vcc
	v_or_b32_e32 v149, 19, v147
	v_sub_u32_e32 v150, v149, v143
	v_cmp_gt_u32_e32 vcc, 16, v150
	v_add_f32_e32 v75, v75, v251
	s_and_b64 vcc, s[0:1], vcc
	v_cndmask_b32_e32 v75, v188, v75, vcc
	v_or_b32_e32 v149, 24, v147
	v_sub_u32_e32 v150, v149, v143
	v_cmp_gt_u32_e32 vcc, 16, v150
	v_add_f32_e32 v76, v76, v252
	s_and_b64 vcc, s[0:1], vcc
	v_cndmask_b32_e32 v76, v188, v76, vcc
	v_or_b32_e32 v149, 25, v147
	v_sub_u32_e32 v150, v149, v143
	v_cmp_gt_u32_e32 vcc, 16, v150
	v_add_f32_e32 v77, v77, v253
	s_and_b64 vcc, s[0:1], vcc
	v_cndmask_b32_e32 v77, v188, v77, vcc
	v_or_b32_e32 v149, 26, v147
	v_sub_u32_e32 v150, v149, v143
	v_cmp_gt_u32_e32 vcc, 16, v150
	v_add_f32_e32 v78, v78, v254
	s_and_b64 vcc, s[0:1], vcc
	v_cndmask_b32_e32 v78, v188, v78, vcc
	v_or_b32_e32 v149, 27, v147
	v_sub_u32_e32 v150, v149, v143
	v_cmp_gt_u32_e32 vcc, 16, v150
	v_add_f32_e32 v79, v79, v255
	s_and_b64 vcc, s[0:1], vcc
	v_cndmask_b32_e32 v79, v188, v79, vcc
